# ff1 GEMM epilogue: the 8 per-row-group norm-statistic loads issued together at epilogue start (one wait) instead of one load+full drain per row group
# baseline (speedup 1.0000x reference)
.LBB0_2128:
	s_lshl_b32 s0, s8, 8
	s_add_i32 s13, s0, s90
	s_lshl_b32 s0, s9, 8
	v_mov_b32_e32 v156, v160
	v_mov_b32_e32 v157, v161
	s_or_b32 s0, s0, s91
	s_mov_b64 s[34:35], -1
	v_lshl_add_u32 v168, v157, 3, s0
	s_lshl_b32 s0, s8, 10
	s_and_b32 s0, s0, 0xfffff000
	s_addk_i32 s0, 0xd000
	s_cmp_gt_i32 s8, 15
	s_cselect_b32 s96, s0, 0
	v_add_u32_e32 v158, s13, v156
	s_lshl_b64 s[0:1], s[96:97], 2
	v_lshlrev_b32_e32 v156, 2, v157
	v_ashrrev_i32_e32 v159, 31, v158
	s_add_u32 s0, s88, s0
	v_ashrrev_i32_e32 v157, 31, v156
	v_lshlrev_b64 v[164:165], 6, v[158:159]
	s_addc_u32 s1, s89, s1
	v_ashrrev_i32_e32 v169, 31, v168
	v_lshl_add_u64 v[164:165], s[22:23], 0, v[164:165]
	v_lshlrev_b64 v[156:157], 2, v[156:157]
	v_lshl_add_u64 v[32:33], v[168:169], 2, s[0:1]
	v_lshl_add_u64 v[164:165], v[164:165], 0, v[156:157]
	flat_load_dwordx4 v[44:47], v[32:33]
	flat_load_dwordx4 v[40:43], v[32:33] offset:16
	flat_load_dwordx4 v[36:39], v[32:33] offset:512
	s_nop 0
	flat_load_dwordx4 v[32:35], v[32:33] offset:528
	s_nop 0
	flat_load_dwordx4 v[164:167], v[164:165]
	v_add_u32_e32 v172, 16, v158
	v_ashrrev_i32_e32 v173, 31, v172
	v_lshlrev_b64 v[172:173], 6, v[172:173]
	v_lshl_add_u64 v[172:173], s[22:23], 0, v[172:173]
	v_lshl_add_u64 v[172:173], v[172:173], 0, v[156:157]
	global_load_dwordx4 v[172:175], v[172:173], off
	v_add_u32_e32 v176, 32, v158
	v_ashrrev_i32_e32 v177, 31, v176
	v_lshlrev_b64 v[176:177], 6, v[176:177]
	v_lshl_add_u64 v[176:177], s[22:23], 0, v[176:177]
	v_lshl_add_u64 v[176:177], v[176:177], 0, v[156:157]
	global_load_dwordx4 v[176:179], v[176:177], off
	v_add_u32_e32 v184, 48, v158
	v_ashrrev_i32_e32 v185, 31, v184
	v_lshlrev_b64 v[184:185], 6, v[184:185]
	v_lshl_add_u64 v[184:185], s[22:23], 0, v[184:185]
	v_lshl_add_u64 v[184:185], v[184:185], 0, v[156:157]
	global_load_dwordx4 v[184:187], v[184:185], off
	v_add_u32_e32 v196, 0x80, v158
	v_ashrrev_i32_e32 v197, 31, v196
	v_lshlrev_b64 v[196:197], 6, v[196:197]
	v_lshl_add_u64 v[196:197], s[22:23], 0, v[196:197]
	v_lshl_add_u64 v[196:197], v[196:197], 0, v[156:157]
	global_load_dwordx4 v[196:199], v[196:197], off
	v_add_u32_e32 v200, 0x90, v158
	v_ashrrev_i32_e32 v201, 31, v200
	v_lshlrev_b64 v[200:201], 6, v[200:201]
	v_lshl_add_u64 v[200:201], s[22:23], 0, v[200:201]
	v_lshl_add_u64 v[200:201], v[200:201], 0, v[156:157]
	global_load_dwordx4 v[200:203], v[200:201], off
	v_add_u32_e32 v204, 0xa0, v158
	v_ashrrev_i32_e32 v205, 31, v204
	v_lshlrev_b64 v[204:205], 6, v[204:205]
	v_lshl_add_u64 v[204:205], s[22:23], 0, v[204:205]
	v_lshl_add_u64 v[204:205], v[204:205], 0, v[156:157]
	global_load_dwordx4 v[204:207], v[204:205], off
	v_add_u32_e32 v216, 0xb0, v158
	v_ashrrev_i32_e32 v217, 31, v216
	v_lshlrev_b64 v[216:217], 6, v[216:217]
	v_lshl_add_u64 v[216:217], s[22:23], 0, v[216:217]
	v_lshl_add_u64 v[216:217], v[216:217], 0, v[156:157]
	global_load_dwordx4 v[216:219], v[216:217], off
	s_waitcnt vmcnt(0) lgkmcnt(0)
	v_add_f32_e32 v164, v164, v165
	v_add_f32_e32 v165, v166, v167
	v_add_f32_e32 v164, v164, v165
	v_mov_b32_e32 v165, v164
	s_nop 1
	v_permlane16_swap_b32_e32 v164, v165
	v_add_f32_e32 v164, v164, v165
	v_mov_b32_e32 v165, v164
	s_nop 1
	v_permlane32_swap_b32_e32 v164, v165
	v_add_f32_e32 v164, v164, v165
	v_fmamk_f32 v164, v164, 0x3a800000, v229
	v_cmp_gt_f32_e32 vcc, s55, v164
	v_mul_f32_e32 v165, 0x4b800000, v164
	v_lshlrev_b64 v[166:167], 13, v[158:159]
	v_cndmask_b32_e32 v164, v164, v165, vcc
	v_rsq_f32_e32 v164, v164
	s_nop 0
	v_mul_f32_e32 v165, 0x45800000, v164
	v_cndmask_b32_e32 v164, v164, v165, vcc
	v_pk_fma_f32 v[144:145], v[144:145], v[164:165], v[46:47] op_sel_hi:[1,0,1]
	v_pk_fma_f32 v[142:143], v[142:143], v[164:165], v[44:45] op_sel_hi:[1,0,1]
	v_pk_fma_f32 v[138:139], v[138:139], v[164:165], v[40:41] op_sel_hi:[1,0,1]
	v_pk_fma_f32 v[140:141], v[140:141], v[164:165], v[42:43] op_sel_hi:[1,0,1]
	v_max_f32_e32 v142, 0, v142
	v_max_f32_e32 v138, 0, v138
	v_max_f32_e32 v143, 0, v143
	v_max_f32_e32 v139, 0, v139
	v_max_f32_e32 v144, 0, v144
	v_max_f32_e32 v145, 0, v145
	v_pk_mul_f32 v[142:143], v[142:143], v[142:143]
	v_pk_mul_f32 v[138:139], v[138:139], v[138:139]
	v_max_f32_e32 v140, 0, v140
	v_max_f32_e32 v141, 0, v141
	v_pk_mul_f32 v[144:145], v[144:145], v[144:145]
	v_pk_mul_f32 v[170:171], v[140:141], v[140:141]
	v_cvt_pk_bf16_f32 v140, v142, v143
	v_cvt_pk_bf16_f32 v141, v144, v145
	v_cvt_pk_bf16_f32 v142, v138, v139
	v_lshl_add_u64 v[144:145], s[20:21], 0, v[166:167]
	v_lshlrev_b64 v[138:139], 1, v[168:169]
	v_pk_fma_f32 v[130:131], v[130:131], v[164:165], v[32:33] op_sel_hi:[1,0,1]
	v_cvt_pk_bf16_f32 v143, v170, v171
	v_lshl_add_u64 v[144:145], v[144:145], 0, v[138:139]
	v_pk_fma_f32 v[136:137], v[136:137], v[164:165], v[38:39] op_sel_hi:[1,0,1]
	v_pk_fma_f32 v[134:135], v[134:135], v[164:165], v[36:37] op_sel_hi:[1,0,1]
	v_pk_fma_f32 v[132:133], v[132:133], v[164:165], v[34:35] op_sel_hi:[1,0,1]
	v_max_f32_e32 v130, 0, v130
	v_max_f32_e32 v131, 0, v131
	flat_store_dwordx4 v[144:145], v[140:143]
	v_max_f32_e32 v134, 0, v134
	v_max_f32_e32 v135, 0, v135
	v_pk_mul_f32 v[140:141], v[130:131], v[130:131]
	v_max_f32_e32 v130, 0, v136
	v_max_f32_e32 v132, 0, v132
	v_max_f32_e32 v131, 0, v137
	v_max_f32_e32 v133, 0, v133
	v_pk_mul_f32 v[134:135], v[134:135], v[134:135]
	v_pk_mul_f32 v[136:137], v[130:131], v[130:131]
	v_pk_mul_f32 v[142:143], v[132:133], v[132:133]
	v_cvt_pk_bf16_f32 v130, v134, v135
	v_cvt_pk_bf16_f32 v131, v136, v137
	v_cvt_pk_bf16_f32 v132, v140, v141
	v_cvt_pk_bf16_f32 v133, v142, v143
	flat_store_dwordx4 v[144:145], v[130:133] offset:256
	s_nop 1
	v_add_u32_e32 v130, 16, v158
	v_ashrrev_i32_e32 v131, 31, v130
	v_lshlrev_b64 v[130:131], 13, v[130:131]
	v_add_f32_e32 v132, v172, v173
	v_add_f32_e32 v133, v174, v175
	v_add_f32_e32 v132, v132, v133
	v_mov_b32_e32 v133, v132
	s_nop 1
	v_permlane16_swap_b32_e32 v132, v133
	v_add_f32_e32 v132, v132, v133
	v_mov_b32_e32 v133, v132
	s_nop 1
	v_permlane32_swap_b32_e32 v132, v133
	v_add_f32_e32 v132, v132, v133
	v_fmamk_f32 v132, v132, 0x3a800000, v229
	v_cmp_gt_f32_e32 vcc, s55, v132
	v_mul_f32_e32 v133, 0x4b800000, v132
	s_nop 0
	v_cndmask_b32_e32 v132, v132, v133, vcc
	v_rsq_f32_e32 v132, v132
	s_nop 0
	v_mul_f32_e32 v133, 0x45800000, v132
	v_cndmask_b32_e32 v132, v132, v133, vcc
	v_pk_fma_f32 v[126:127], v[126:127], v[132:133], v[44:45] op_sel_hi:[1,0,1]
	v_pk_fma_f32 v[122:123], v[122:123], v[132:133], v[40:41] op_sel_hi:[1,0,1]
	v_pk_fma_f32 v[128:129], v[128:129], v[132:133], v[46:47] op_sel_hi:[1,0,1]
	v_pk_fma_f32 v[124:125], v[124:125], v[132:133], v[42:43] op_sel_hi:[1,0,1]
	v_max_f32_e32 v126, 0, v126
	v_max_f32_e32 v122, 0, v122
	v_max_f32_e32 v127, 0, v127
	v_max_f32_e32 v123, 0, v123
	v_pk_mul_f32 v[126:127], v[126:127], v[126:127]
	v_pk_mul_f32 v[134:135], v[122:123], v[122:123]
	v_max_f32_e32 v122, 0, v128
	v_max_f32_e32 v124, 0, v124
	v_max_f32_e32 v123, 0, v129
	v_max_f32_e32 v125, 0, v125
	v_pk_mul_f32 v[128:129], v[122:123], v[122:123]
	v_pk_mul_f32 v[136:137], v[124:125], v[124:125]
	v_cvt_pk_bf16_f32 v122, v126, v127
	v_lshl_add_u64 v[126:127], s[20:21], 0, v[130:131]
	v_pk_fma_f32 v[114:115], v[114:115], v[132:133], v[32:33] op_sel_hi:[1,0,1]
	v_cvt_pk_bf16_f32 v123, v128, v129
	v_cvt_pk_bf16_f32 v124, v134, v135
	v_cvt_pk_bf16_f32 v125, v136, v137
	v_lshl_add_u64 v[126:127], v[126:127], 0, v[138:139]
	v_pk_fma_f32 v[120:121], v[120:121], v[132:133], v[38:39] op_sel_hi:[1,0,1]
	v_pk_fma_f32 v[118:119], v[118:119], v[132:133], v[36:37] op_sel_hi:[1,0,1]
	v_pk_fma_f32 v[116:117], v[116:117], v[132:133], v[34:35] op_sel_hi:[1,0,1]
	v_max_f32_e32 v114, 0, v114
	v_max_f32_e32 v115, 0, v115
	flat_store_dwordx4 v[126:127], v[122:125]
	v_max_f32_e32 v118, 0, v118
	v_max_f32_e32 v119, 0, v119
	v_pk_mul_f32 v[122:123], v[114:115], v[114:115]
	v_max_f32_e32 v114, 0, v120
	v_max_f32_e32 v116, 0, v116
	v_max_f32_e32 v115, 0, v121
	v_max_f32_e32 v117, 0, v117
	v_pk_mul_f32 v[118:119], v[118:119], v[118:119]
	v_pk_mul_f32 v[120:121], v[114:115], v[114:115]
	v_pk_mul_f32 v[124:125], v[116:117], v[116:117]
	v_cvt_pk_bf16_f32 v114, v118, v119
	v_cvt_pk_bf16_f32 v115, v120, v121
	v_cvt_pk_bf16_f32 v116, v122, v123
	v_cvt_pk_bf16_f32 v117, v124, v125
	flat_store_dwordx4 v[126:127], v[114:117] offset:256
	s_nop 1
	v_add_u32_e32 v114, 32, v158
	v_ashrrev_i32_e32 v115, 31, v114
	v_lshlrev_b64 v[114:115], 13, v[114:115]
	v_add_f32_e32 v116, v176, v177
	v_add_f32_e32 v117, v178, v179
	v_add_f32_e32 v116, v116, v117
	v_mov_b32_e32 v117, v116
	s_nop 1
	v_permlane16_swap_b32_e32 v116, v117
	v_add_f32_e32 v116, v116, v117
	v_mov_b32_e32 v117, v116
	s_nop 1
	v_permlane32_swap_b32_e32 v116, v117
	v_add_f32_e32 v116, v116, v117
	v_fmamk_f32 v116, v116, 0x3a800000, v229
	v_cmp_gt_f32_e32 vcc, s55, v116
	v_mul_f32_e32 v117, 0x4b800000, v116
	s_nop 0
	v_cndmask_b32_e32 v116, v116, v117, vcc
	v_rsq_f32_e32 v116, v116
	s_nop 0
	v_mul_f32_e32 v117, 0x45800000, v116
	v_cndmask_b32_e32 v116, v116, v117, vcc
	v_pk_fma_f32 v[110:111], v[110:111], v[116:117], v[44:45] op_sel_hi:[1,0,1]
	v_pk_fma_f32 v[106:107], v[106:107], v[116:117], v[40:41] op_sel_hi:[1,0,1]
	v_pk_fma_f32 v[112:113], v[112:113], v[116:117], v[46:47] op_sel_hi:[1,0,1]
	v_pk_fma_f32 v[108:109], v[108:109], v[116:117], v[42:43] op_sel_hi:[1,0,1]
	v_max_f32_e32 v110, 0, v110
	v_max_f32_e32 v106, 0, v106
	v_max_f32_e32 v111, 0, v111
	v_max_f32_e32 v107, 0, v107
	v_pk_mul_f32 v[110:111], v[110:111], v[110:111]
	v_pk_mul_f32 v[118:119], v[106:107], v[106:107]
	v_max_f32_e32 v106, 0, v112
	v_max_f32_e32 v108, 0, v108
	v_max_f32_e32 v107, 0, v113
	v_max_f32_e32 v109, 0, v109
	v_pk_mul_f32 v[112:113], v[106:107], v[106:107]
	v_pk_mul_f32 v[120:121], v[108:109], v[108:109]
	v_cvt_pk_bf16_f32 v106, v110, v111
	v_lshl_add_u64 v[110:111], s[20:21], 0, v[114:115]
	v_pk_fma_f32 v[98:99], v[98:99], v[116:117], v[32:33] op_sel_hi:[1,0,1]
	v_cvt_pk_bf16_f32 v107, v112, v113
	v_cvt_pk_bf16_f32 v108, v118, v119
	v_cvt_pk_bf16_f32 v109, v120, v121
	v_lshl_add_u64 v[110:111], v[110:111], 0, v[138:139]
	v_pk_fma_f32 v[104:105], v[104:105], v[116:117], v[38:39] op_sel_hi:[1,0,1]
	v_pk_fma_f32 v[102:103], v[102:103], v[116:117], v[36:37] op_sel_hi:[1,0,1]
	v_pk_fma_f32 v[100:101], v[100:101], v[116:117], v[34:35] op_sel_hi:[1,0,1]
	v_max_f32_e32 v98, 0, v98
	v_max_f32_e32 v99, 0, v99
	flat_store_dwordx4 v[110:111], v[106:109]
	v_max_f32_e32 v102, 0, v102
	v_max_f32_e32 v103, 0, v103
	v_pk_mul_f32 v[106:107], v[98:99], v[98:99]
	v_max_f32_e32 v98, 0, v104
	v_max_f32_e32 v100, 0, v100
	v_max_f32_e32 v99, 0, v105
	v_max_f32_e32 v101, 0, v101
	v_pk_mul_f32 v[102:103], v[102:103], v[102:103]
	v_pk_mul_f32 v[104:105], v[98:99], v[98:99]
	v_pk_mul_f32 v[108:109], v[100:101], v[100:101]
	v_cvt_pk_bf16_f32 v98, v102, v103
	v_cvt_pk_bf16_f32 v99, v104, v105
	v_cvt_pk_bf16_f32 v100, v106, v107
	v_cvt_pk_bf16_f32 v101, v108, v109
	flat_store_dwordx4 v[110:111], v[98:101] offset:256
	s_nop 1
	v_add_u32_e32 v98, 48, v158
	v_ashrrev_i32_e32 v99, 31, v98
	v_lshlrev_b64 v[98:99], 13, v[98:99]
	v_add_f32_e32 v100, v184, v185
	v_add_f32_e32 v101, v186, v187
	v_add_f32_e32 v100, v100, v101
	v_mov_b32_e32 v101, v100
	s_nop 1
	v_permlane16_swap_b32_e32 v100, v101
	v_add_f32_e32 v100, v100, v101
	v_mov_b32_e32 v101, v100
	s_nop 1
	v_permlane32_swap_b32_e32 v100, v101
	v_add_f32_e32 v100, v100, v101
	v_fmamk_f32 v100, v100, 0x3a800000, v229
	v_cmp_gt_f32_e32 vcc, s55, v100
	v_mul_f32_e32 v101, 0x4b800000, v100
	s_nop 0
	v_cndmask_b32_e32 v100, v100, v101, vcc
	v_rsq_f32_e32 v100, v100
	s_nop 0
	v_mul_f32_e32 v101, 0x45800000, v100
	v_cndmask_b32_e32 v100, v100, v101, vcc
	v_pk_fma_f32 v[94:95], v[94:95], v[100:101], v[44:45] op_sel_hi:[1,0,1]
	v_pk_fma_f32 v[90:91], v[90:91], v[100:101], v[40:41] op_sel_hi:[1,0,1]
	v_pk_fma_f32 v[96:97], v[96:97], v[100:101], v[46:47] op_sel_hi:[1,0,1]
	v_pk_fma_f32 v[92:93], v[92:93], v[100:101], v[42:43] op_sel_hi:[1,0,1]
	v_max_f32_e32 v94, 0, v94
	v_max_f32_e32 v90, 0, v90
	v_max_f32_e32 v95, 0, v95
	v_max_f32_e32 v91, 0, v91
	v_pk_mul_f32 v[94:95], v[94:95], v[94:95]
	v_pk_mul_f32 v[102:103], v[90:91], v[90:91]
	v_max_f32_e32 v90, 0, v96
	v_max_f32_e32 v92, 0, v92
	v_max_f32_e32 v91, 0, v97
	v_max_f32_e32 v93, 0, v93
	v_pk_mul_f32 v[96:97], v[90:91], v[90:91]
	v_pk_mul_f32 v[104:105], v[92:93], v[92:93]
	v_cvt_pk_bf16_f32 v90, v94, v95
	v_lshl_add_u64 v[94:95], s[20:21], 0, v[98:99]
	v_pk_fma_f32 v[82:83], v[82:83], v[100:101], v[32:33] op_sel_hi:[1,0,1]
	v_cvt_pk_bf16_f32 v91, v96, v97
	v_cvt_pk_bf16_f32 v92, v102, v103
	v_cvt_pk_bf16_f32 v93, v104, v105
	v_lshl_add_u64 v[94:95], v[94:95], 0, v[138:139]
	v_pk_fma_f32 v[88:89], v[88:89], v[100:101], v[38:39] op_sel_hi:[1,0,1]
	v_pk_fma_f32 v[86:87], v[86:87], v[100:101], v[36:37] op_sel_hi:[1,0,1]
	v_pk_fma_f32 v[84:85], v[84:85], v[100:101], v[34:35] op_sel_hi:[1,0,1]
	v_max_f32_e32 v82, 0, v82
	v_max_f32_e32 v83, 0, v83
	flat_store_dwordx4 v[94:95], v[90:93]
	v_max_f32_e32 v86, 0, v86
	v_max_f32_e32 v87, 0, v87
	v_pk_mul_f32 v[90:91], v[82:83], v[82:83]
	v_max_f32_e32 v82, 0, v88
	v_max_f32_e32 v84, 0, v84
	v_max_f32_e32 v83, 0, v89
	v_max_f32_e32 v85, 0, v85
	v_pk_mul_f32 v[86:87], v[86:87], v[86:87]
	v_pk_mul_f32 v[88:89], v[82:83], v[82:83]
	v_pk_mul_f32 v[92:93], v[84:85], v[84:85]
	v_cvt_pk_bf16_f32 v82, v86, v87
	v_cvt_pk_bf16_f32 v83, v88, v89
	v_cvt_pk_bf16_f32 v84, v90, v91
	v_cvt_pk_bf16_f32 v85, v92, v93
	flat_store_dwordx4 v[94:95], v[82:85] offset:256
	s_nop 1
	v_add_u32_e32 v82, 0x80, v158
	v_ashrrev_i32_e32 v83, 31, v82
	v_lshlrev_b64 v[82:83], 13, v[82:83]
	v_add_f32_e32 v84, v196, v197
	v_add_f32_e32 v85, v198, v199
	v_add_f32_e32 v84, v84, v85
	v_mov_b32_e32 v85, v84
	s_nop 1
	v_permlane16_swap_b32_e32 v84, v85
	v_add_f32_e32 v84, v84, v85
	v_mov_b32_e32 v85, v84
	s_nop 1
	v_permlane32_swap_b32_e32 v84, v85
	v_add_f32_e32 v84, v84, v85
	v_fmamk_f32 v84, v84, 0x3a800000, v229
	v_cmp_gt_f32_e32 vcc, s55, v84
	v_mul_f32_e32 v85, 0x4b800000, v84
	s_nop 0
	v_cndmask_b32_e32 v84, v84, v85, vcc
	v_rsq_f32_e32 v84, v84
	s_nop 0
	v_mul_f32_e32 v85, 0x45800000, v84
	v_cndmask_b32_e32 v84, v84, v85, vcc
	v_pk_fma_f32 v[78:79], v[78:79], v[84:85], v[44:45] op_sel_hi:[1,0,1]
	v_pk_fma_f32 v[74:75], v[74:75], v[84:85], v[40:41] op_sel_hi:[1,0,1]
	v_pk_fma_f32 v[80:81], v[80:81], v[84:85], v[46:47] op_sel_hi:[1,0,1]
	v_pk_fma_f32 v[76:77], v[76:77], v[84:85], v[42:43] op_sel_hi:[1,0,1]
	v_max_f32_e32 v78, 0, v78
	v_max_f32_e32 v74, 0, v74
	v_max_f32_e32 v79, 0, v79
	v_max_f32_e32 v75, 0, v75
	v_pk_mul_f32 v[78:79], v[78:79], v[78:79]
	v_pk_mul_f32 v[86:87], v[74:75], v[74:75]
	v_max_f32_e32 v74, 0, v80
	v_max_f32_e32 v76, 0, v76
	v_max_f32_e32 v75, 0, v81
	v_max_f32_e32 v77, 0, v77
	v_pk_mul_f32 v[80:81], v[74:75], v[74:75]
	v_pk_mul_f32 v[88:89], v[76:77], v[76:77]
	v_cvt_pk_bf16_f32 v74, v78, v79
	v_lshl_add_u64 v[78:79], s[20:21], 0, v[82:83]
	v_pk_fma_f32 v[66:67], v[66:67], v[84:85], v[32:33] op_sel_hi:[1,0,1]
	v_cvt_pk_bf16_f32 v75, v80, v81
	v_cvt_pk_bf16_f32 v76, v86, v87
	v_cvt_pk_bf16_f32 v77, v88, v89
	v_lshl_add_u64 v[78:79], v[78:79], 0, v[138:139]
	v_pk_fma_f32 v[72:73], v[72:73], v[84:85], v[38:39] op_sel_hi:[1,0,1]
	v_pk_fma_f32 v[70:71], v[70:71], v[84:85], v[36:37] op_sel_hi:[1,0,1]
	v_pk_fma_f32 v[68:69], v[68:69], v[84:85], v[34:35] op_sel_hi:[1,0,1]
	v_max_f32_e32 v66, 0, v66
	v_max_f32_e32 v67, 0, v67
	flat_store_dwordx4 v[78:79], v[74:77]
	v_max_f32_e32 v70, 0, v70
	v_max_f32_e32 v71, 0, v71
	v_pk_mul_f32 v[74:75], v[66:67], v[66:67]
	v_max_f32_e32 v66, 0, v72
	v_max_f32_e32 v68, 0, v68
	v_max_f32_e32 v67, 0, v73
	v_max_f32_e32 v69, 0, v69
	v_pk_mul_f32 v[70:71], v[70:71], v[70:71]
	v_pk_mul_f32 v[72:73], v[66:67], v[66:67]
	v_pk_mul_f32 v[76:77], v[68:69], v[68:69]
	v_cvt_pk_bf16_f32 v66, v70, v71
	v_cvt_pk_bf16_f32 v67, v72, v73
	v_cvt_pk_bf16_f32 v68, v74, v75
	v_cvt_pk_bf16_f32 v69, v76, v77
	flat_store_dwordx4 v[78:79], v[66:69] offset:256
	s_nop 1
	v_add_u32_e32 v66, 0x90, v158
	v_ashrrev_i32_e32 v67, 31, v66
	v_lshlrev_b64 v[66:67], 13, v[66:67]
	v_add_f32_e32 v68, v200, v201
	v_add_f32_e32 v69, v202, v203
	v_add_f32_e32 v68, v68, v69
	v_mov_b32_e32 v69, v68
	s_nop 1
	v_permlane16_swap_b32_e32 v68, v69
	v_add_f32_e32 v68, v68, v69
	v_mov_b32_e32 v69, v68
	s_nop 1
	v_permlane32_swap_b32_e32 v68, v69
	v_add_f32_e32 v68, v68, v69
	v_fmamk_f32 v68, v68, 0x3a800000, v229
	v_cmp_gt_f32_e32 vcc, s55, v68
	v_mul_f32_e32 v69, 0x4b800000, v68
	s_nop 0
	v_cndmask_b32_e32 v68, v68, v69, vcc
	v_rsq_f32_e32 v68, v68
	s_nop 0
	v_mul_f32_e32 v69, 0x45800000, v68
	v_cndmask_b32_e32 v68, v68, v69, vcc
	v_pk_fma_f32 v[60:61], v[60:61], v[68:69], v[44:45] op_sel_hi:[1,0,1]
	v_pk_fma_f32 v[56:57], v[56:57], v[68:69], v[40:41] op_sel_hi:[1,0,1]
	v_pk_fma_f32 v[62:63], v[62:63], v[68:69], v[46:47] op_sel_hi:[1,0,1]
	v_pk_fma_f32 v[58:59], v[58:59], v[68:69], v[42:43] op_sel_hi:[1,0,1]
	v_max_f32_e32 v60, 0, v60
	v_max_f32_e32 v56, 0, v56
	v_max_f32_e32 v61, 0, v61
	v_max_f32_e32 v57, 0, v57
	v_pk_mul_f32 v[60:61], v[60:61], v[60:61]
	v_pk_mul_f32 v[70:71], v[56:57], v[56:57]
	v_max_f32_e32 v56, 0, v62
	v_max_f32_e32 v58, 0, v58
	v_max_f32_e32 v57, 0, v63
	v_max_f32_e32 v59, 0, v59
	v_pk_mul_f32 v[62:63], v[56:57], v[56:57]
	v_pk_mul_f32 v[72:73], v[58:59], v[58:59]
	v_cvt_pk_bf16_f32 v56, v60, v61
	v_lshl_add_u64 v[60:61], s[20:21], 0, v[66:67]
	v_pk_fma_f32 v[48:49], v[48:49], v[68:69], v[32:33] op_sel_hi:[1,0,1]
	v_cvt_pk_bf16_f32 v57, v62, v63
	v_cvt_pk_bf16_f32 v58, v70, v71
	v_cvt_pk_bf16_f32 v59, v72, v73
	v_lshl_add_u64 v[60:61], v[60:61], 0, v[138:139]
	v_pk_fma_f32 v[54:55], v[54:55], v[68:69], v[38:39] op_sel_hi:[1,0,1]
	v_pk_fma_f32 v[52:53], v[52:53], v[68:69], v[36:37] op_sel_hi:[1,0,1]
	v_pk_fma_f32 v[50:51], v[50:51], v[68:69], v[34:35] op_sel_hi:[1,0,1]
	v_max_f32_e32 v48, 0, v48
	v_max_f32_e32 v49, 0, v49
	flat_store_dwordx4 v[60:61], v[56:59]
	v_max_f32_e32 v52, 0, v52
	v_max_f32_e32 v53, 0, v53
	v_pk_mul_f32 v[56:57], v[48:49], v[48:49]
	v_max_f32_e32 v48, 0, v54
	v_max_f32_e32 v50, 0, v50
	v_max_f32_e32 v49, 0, v55
	v_max_f32_e32 v51, 0, v51
	v_pk_mul_f32 v[52:53], v[52:53], v[52:53]
	v_pk_mul_f32 v[54:55], v[48:49], v[48:49]
	v_pk_mul_f32 v[58:59], v[50:51], v[50:51]
	v_cvt_pk_bf16_f32 v48, v52, v53
	v_cvt_pk_bf16_f32 v49, v54, v55
	v_cvt_pk_bf16_f32 v50, v56, v57
	v_cvt_pk_bf16_f32 v51, v58, v59
	flat_store_dwordx4 v[60:61], v[48:51] offset:256
	s_nop 1
	v_add_u32_e32 v48, 0xa0, v158
	v_ashrrev_i32_e32 v49, 31, v48
	v_lshlrev_b64 v[48:49], 13, v[48:49]
	v_add_f32_e32 v50, v204, v205
	v_add_f32_e32 v51, v206, v207
	v_add_f32_e32 v50, v50, v51
	v_mov_b32_e32 v51, v50
	s_nop 1
	v_permlane16_swap_b32_e32 v50, v51
	v_add_f32_e32 v50, v50, v51
	v_mov_b32_e32 v51, v50
	s_nop 1
	v_permlane32_swap_b32_e32 v50, v51
	v_add_f32_e32 v50, v50, v51
	v_fmamk_f32 v50, v50, 0x3a800000, v229
	v_cmp_gt_f32_e32 vcc, s55, v50
	v_mul_f32_e32 v51, 0x4b800000, v50
	s_nop 0
	v_cndmask_b32_e32 v50, v50, v51, vcc
	v_rsq_f32_e32 v50, v50
	s_nop 0
	v_mul_f32_e32 v51, 0x45800000, v50
	v_cndmask_b32_e32 v50, v50, v51, vcc
	v_pk_fma_f32 v[28:29], v[28:29], v[50:51], v[44:45] op_sel_hi:[1,0,1]
	v_pk_fma_f32 v[24:25], v[24:25], v[50:51], v[40:41] op_sel_hi:[1,0,1]
	v_pk_fma_f32 v[30:31], v[30:31], v[50:51], v[46:47] op_sel_hi:[1,0,1]
	v_pk_fma_f32 v[26:27], v[26:27], v[50:51], v[42:43] op_sel_hi:[1,0,1]
	v_max_f32_e32 v28, 0, v28
	v_max_f32_e32 v24, 0, v24
	v_max_f32_e32 v29, 0, v29
	v_max_f32_e32 v25, 0, v25
	v_pk_mul_f32 v[28:29], v[28:29], v[28:29]
	v_pk_mul_f32 v[52:53], v[24:25], v[24:25]
	v_max_f32_e32 v24, 0, v30
	v_max_f32_e32 v26, 0, v26
	v_max_f32_e32 v25, 0, v31
	v_max_f32_e32 v27, 0, v27
	v_pk_mul_f32 v[30:31], v[24:25], v[24:25]
	v_pk_mul_f32 v[54:55], v[26:27], v[26:27]
	v_cvt_pk_bf16_f32 v24, v28, v29
	v_lshl_add_u64 v[28:29], s[20:21], 0, v[48:49]
	v_pk_fma_f32 v[16:17], v[16:17], v[50:51], v[32:33] op_sel_hi:[1,0,1]
	v_cvt_pk_bf16_f32 v25, v30, v31
	v_cvt_pk_bf16_f32 v26, v52, v53
	v_cvt_pk_bf16_f32 v27, v54, v55
	v_lshl_add_u64 v[28:29], v[28:29], 0, v[138:139]
	v_pk_fma_f32 v[22:23], v[22:23], v[50:51], v[38:39] op_sel_hi:[1,0,1]
	v_pk_fma_f32 v[20:21], v[20:21], v[50:51], v[36:37] op_sel_hi:[1,0,1]
	v_pk_fma_f32 v[18:19], v[18:19], v[50:51], v[34:35] op_sel_hi:[1,0,1]
	v_max_f32_e32 v16, 0, v16
	v_max_f32_e32 v17, 0, v17
	flat_store_dwordx4 v[28:29], v[24:27]
	v_max_f32_e32 v20, 0, v20
	v_max_f32_e32 v21, 0, v21
	v_pk_mul_f32 v[24:25], v[16:17], v[16:17]
	v_max_f32_e32 v16, 0, v22
	v_max_f32_e32 v18, 0, v18
	v_max_f32_e32 v17, 0, v23
	v_max_f32_e32 v19, 0, v19
	v_pk_mul_f32 v[20:21], v[20:21], v[20:21]
	v_pk_mul_f32 v[22:23], v[16:17], v[16:17]
	v_pk_mul_f32 v[26:27], v[18:19], v[18:19]
	v_cvt_pk_bf16_f32 v16, v20, v21
	v_cvt_pk_bf16_f32 v17, v22, v23
	v_cvt_pk_bf16_f32 v18, v24, v25
	v_cvt_pk_bf16_f32 v19, v26, v27
	flat_store_dwordx4 v[28:29], v[16:19] offset:256
	s_nop 1
	v_add_u32_e32 v16, 0xb0, v158
	v_ashrrev_i32_e32 v17, 31, v16
	v_lshlrev_b64 v[16:17], 13, v[16:17]
	v_add_f32_e32 v18, v216, v217
	v_add_f32_e32 v19, v218, v219
	v_add_f32_e32 v18, v18, v19
	v_mov_b32_e32 v19, v18
	s_nop 1
	v_permlane16_swap_b32_e32 v18, v19
	v_add_f32_e32 v18, v18, v19
	v_mov_b32_e32 v19, v18
	s_nop 1
	v_permlane32_swap_b32_e32 v18, v19
	v_add_f32_e32 v18, v18, v19
	v_fmamk_f32 v18, v18, 0x3a800000, v229
	v_cmp_gt_f32_e32 vcc, s55, v18
	v_mul_f32_e32 v19, 0x4b800000, v18
	s_nop 0
	v_cndmask_b32_e32 v18, v18, v19, vcc
	v_rsq_f32_e32 v18, v18
	s_nop 0
	v_mul_f32_e32 v19, 0x45800000, v18
	v_cndmask_b32_e32 v18, v18, v19, vcc
	v_pk_fma_f32 v[12:13], v[12:13], v[18:19], v[44:45] op_sel_hi:[1,0,1]
	v_pk_fma_f32 v[8:9], v[8:9], v[18:19], v[40:41] op_sel_hi:[1,0,1]
	v_pk_fma_f32 v[14:15], v[14:15], v[18:19], v[46:47] op_sel_hi:[1,0,1]
	v_pk_fma_f32 v[10:11], v[10:11], v[18:19], v[42:43] op_sel_hi:[1,0,1]
	v_max_f32_e32 v12, 0, v12
	v_max_f32_e32 v8, 0, v8
	v_max_f32_e32 v13, 0, v13
	v_max_f32_e32 v9, 0, v9
	v_pk_mul_f32 v[12:13], v[12:13], v[12:13]
	v_pk_mul_f32 v[20:21], v[8:9], v[8:9]
	v_max_f32_e32 v8, 0, v14
	v_max_f32_e32 v10, 0, v10
	v_max_f32_e32 v9, 0, v15
	v_max_f32_e32 v11, 0, v11
	v_pk_mul_f32 v[14:15], v[8:9], v[8:9]
	v_pk_mul_f32 v[22:23], v[10:11], v[10:11]
	v_cvt_pk_bf16_f32 v8, v12, v13
	v_lshl_add_u64 v[12:13], s[20:21], 0, v[16:17]
	v_pk_fma_f32 v[0:1], v[0:1], v[18:19], v[32:33] op_sel_hi:[1,0,1]
	v_cvt_pk_bf16_f32 v9, v14, v15
	v_cvt_pk_bf16_f32 v10, v20, v21
	v_cvt_pk_bf16_f32 v11, v22, v23
	v_lshl_add_u64 v[12:13], v[12:13], 0, v[138:139]
	v_pk_fma_f32 v[6:7], v[6:7], v[18:19], v[38:39] op_sel_hi:[1,0,1]
	v_pk_fma_f32 v[4:5], v[4:5], v[18:19], v[36:37] op_sel_hi:[1,0,1]
	v_pk_fma_f32 v[2:3], v[2:3], v[18:19], v[34:35] op_sel_hi:[1,0,1]
	v_max_f32_e32 v0, 0, v0
	v_max_f32_e32 v1, 0, v1
	flat_store_dwordx4 v[12:13], v[8:11]
	v_max_f32_e32 v4, 0, v4
	v_max_f32_e32 v5, 0, v5
	v_pk_mul_f32 v[8:9], v[0:1], v[0:1]
	v_max_f32_e32 v0, 0, v6
	v_max_f32_e32 v2, 0, v2
	v_max_f32_e32 v1, 0, v7
	v_max_f32_e32 v3, 0, v3
	v_pk_mul_f32 v[4:5], v[4:5], v[4:5]
	v_pk_mul_f32 v[6:7], v[0:1], v[0:1]
	v_pk_mul_f32 v[10:11], v[2:3], v[2:3]
	v_cvt_pk_bf16_f32 v0, v4, v5
	v_cvt_pk_bf16_f32 v1, v6, v7
	v_cvt_pk_bf16_f32 v2, v8, v9
	v_cvt_pk_bf16_f32 v3, v10, v11
	s_andn2_b64 vcc, exec, s[6:7]
	flat_store_dwordx4 v[12:13], v[0:3] offset:256
	s_cbranch_vccnz .LBB0_2121
	s_andn2_b64 vcc, exec, s[18:19]
	s_cbranch_vccnz .LBB0_2120
	s_barrier
	s_branch .LBB0_2120
